# FFN-up: hoist next-unit SS rstd loads above epilogue, one counted wait
# speedup vs baseline: 1.0158x; 1.0158x over previous
; __device__ __forceinline__ unsigned pk2(float lo, float hi) { f32x2_t v = {lo, hi}; bf16x2_t b = __builtin_convertvector(v, bf16x2_t); return __builtin_bit_cast(unsigned, b); }
; __device__ __forceinline__ float siluf_(float x) { return x * sigmoidf_(x); }
; #define RSTD_GET(ai, m) __int_as_float(__builtin_amdgcn_ds_bpermute(((m) * 16 + fr) << 2, __float_as_int((ai) ? es1 : es0)))
; __device__ __forceinline__ float row_rstd(const float* SS, int row) {
;     const f32x4* p = (const f32x4*)(SS + (size_t)row * 32);
;     float s = 0.f;
; #pragma unroll
;     for (int j = 0; j < 8; ++j) { const f32x4 a = p[j]; s += (a[0] + a[1]) + (a[2] + a[3]); }
;     return rsqrtf(s * (1.f / 1024.f) + EPS);
;     __device__ __forceinline__ void operator()(EPI_ARGS) const {
;     ...
;             for (int m = 0; m < 4; ++m) {
;                 int row = EPI_ROWS(ai, m); asm volatile("" : "+v"(row)); const float rs = RSTD_GET(ai, m);
;                 float o[8];
; #pragma unroll
;                 for (int n = 0; n < 2; ++n)
; #pragma unroll
;                     for (int e = 0; e < 4; ++e) { const float g = acc[ai][0][m][n][e] * rs, up = acc[ai][1][m][n][e] * rs; o[n * 4 + e] = siluf_(g) * up; }
;                 u32x4 w; w.x = pk2(o[0], o[1]); w.y = pk2(o[2], o[3]); w.z = pk2(o[4], o[5]); w.w = pk2(o[6], o[7]);
;                 *(u32x4*)(T + (size_t)row * FF + u.pn * 128 + wc * 32 + 8 * fq) = w;
.LBB0_899:
	s_lshl_b32 s2, s63, 8
	v_mov_b32_e32 v247, 0
	v_add3_u32 v246, s2, v143, v142
	s_mov_b64 s[2:3], 0x4000
	v_lshlrev_b64 v[246:247], 7, v[246:247]
	v_lshl_add_u64 v[246:247], s[94:95], 0, v[246:247]
	v_lshl_add_u64 v[244:245], v[246:247], 0, s[2:3]
	global_load_dwordx4 v[204:207], v[246:247], off
	global_load_dwordx4 v[208:211], v[246:247], off offset:16
	global_load_dwordx4 v[212:215], v[246:247], off offset:32
	global_load_dwordx4 v[216:219], v[246:247], off offset:48
	global_load_dwordx4 v[220:223], v[246:247], off offset:64
	global_load_dwordx4 v[224:227], v[246:247], off offset:80
	global_load_dwordx4 v[228:231], v[246:247], off offset:96
	global_load_dwordx4 v[232:235], v[246:247], off offset:112
	global_load_dwordx4 v[236:239], v[244:245], off
	global_load_dwordx4 v[240:243], v[244:245], off offset:16
	global_load_dwordx4 v[180:183], v[244:245], off offset:32
	global_load_dwordx4 v[184:187], v[244:245], off offset:48
	global_load_dwordx4 v[190:193], v[244:245], off offset:64
	global_load_dwordx4 v[194:197], v[244:245], off offset:80
	global_load_dwordx4 v[160:163], v[244:245], off offset:96
	global_load_dwordx4 v[244:247], v[244:245], off offset:112
	ds_bpermute_b32 v156, v145, v141
	s_lshl_b32 s26, s26, 8
	v_readlane_b32 s2, v255, 10
	v_add_u32_e32 v154, s26, v144
	v_readlane_b32 s3, v255, 11
	s_waitcnt lgkmcnt(0)
	v_pk_mul_f32 v[124:125], v[124:125], v[156:157] op_sel_hi:[1,0]
	v_mov_b32_e32 v155, v154
	v_mul_f32_e32 v157, 0xbfb8aa3b, v124
	v_exp_f32_e32 v157, v157
	s_andn2_b64 vcc, exec, s[36:37]
	v_add_f32_e32 v157, 1.0, v157
	v_rcp_f32_e32 v158, v157
	v_pk_mul_f32 v[120:121], v[120:121], v[156:157] op_sel_hi:[1,0]
	v_mul_f32_e32 v157, 0xbfb8aa3b, v125
	v_exp_f32_e32 v157, v157
	s_nop 0
	v_add_f32_e32 v157, 1.0, v157
	v_rcp_f32_e32 v159, v157
	v_pk_mul_f32 v[122:123], v[122:123], v[156:157] op_sel_hi:[1,0]
	v_pk_mul_f32 v[116:117], v[116:117], v[156:157] op_sel_hi:[1,0]
	v_pk_mul_f32 v[112:113], v[112:113], v[156:157] op_sel_hi:[1,0]
	v_pk_mul_f32 v[124:125], v[124:125], v[158:159]
	v_pk_mul_f32 v[114:115], v[114:115], v[156:157] op_sel_hi:[1,0]
	v_pk_mul_f32 v[120:121], v[120:121], v[124:125]
	v_pk_mul_f32 v[124:125], v[126:127], v[156:157] op_sel_hi:[1,0]
	s_nop 0
	v_mul_f32_e32 v126, 0xbfb8aa3b, v124
	v_mul_f32_e32 v127, 0xbfb8aa3b, v125
	v_exp_f32_e32 v126, v126
	v_exp_f32_e32 v127, v127
	v_add_f32_e32 v126, 1.0, v126
	v_add_f32_e32 v127, 1.0, v127
	v_rcp_f32_e32 v126, v126
	v_rcp_f32_e32 v127, v127
	s_nop 0
	v_pk_mul_f32 v[124:125], v[124:125], v[126:127]
	s_nop 0
	v_pk_mul_f32 v[122:123], v[122:123], v[124:125]
	v_mul_f32_e32 v124, 0xbfb8aa3b, v116
	v_mul_f32_e32 v125, 0xbfb8aa3b, v117
	v_exp_f32_e32 v124, v124
	v_exp_f32_e32 v125, v125
	v_add_f32_e32 v124, 1.0, v124
	v_add_f32_e32 v125, 1.0, v125
	v_rcp_f32_e32 v124, v124
	v_rcp_f32_e32 v125, v125
	s_nop 0
	v_pk_mul_f32 v[116:117], v[116:117], v[124:125]
	s_nop 0
	v_pk_mul_f32 v[112:113], v[112:113], v[116:117]
	v_pk_mul_f32 v[116:117], v[118:119], v[156:157] op_sel_hi:[1,0]
	s_nop 0
	v_mul_f32_e32 v118, 0xbfb8aa3b, v116
	v_mul_f32_e32 v119, 0xbfb8aa3b, v117
	v_exp_f32_e32 v118, v118
	v_exp_f32_e32 v119, v119
	v_add_f32_e32 v118, 1.0, v118
	v_add_f32_e32 v119, 1.0, v119
	v_rcp_f32_e32 v118, v118
	v_rcp_f32_e32 v119, v119
	s_nop 0
	v_pk_mul_f32 v[116:117], v[116:117], v[118:119]
	s_nop 0
	v_pk_mul_f32 v[118:119], v[114:115], v[116:117]
	v_cvt_pk_bf16_f32 v116, v112, v113
	v_mov_b64_e32 v[112:113], s[2:3]
	v_cvt_pk_bf16_f32 v117, v118, v119
	v_mad_i64_i32 v[118:119], s[2:3], v155, s71, v[112:113]
	s_lshl_b32 s2, s27, 7
	s_ashr_i32 s3, s2, 31
	s_lshl_b64 s[2:3], s[2:3], 1
	v_lshl_add_u64 v[118:119], v[118:119], 0, s[2:3]
	v_lshl_add_u64 v[118:119], v[118:119], 0, s[4:5]
	v_cvt_pk_bf16_f32 v114, v120, v121
	v_cvt_pk_bf16_f32 v115, v122, v123
	v_lshl_add_u64 v[118:119], v[118:119], 0, v[168:169]
	global_store_dwordx4 v[118:119], v[114:117], off
	ds_bpermute_b32 v116, v148, v141
	s_waitcnt lgkmcnt(0)
	v_pk_mul_f32 v[108:109], v[108:109], v[116:117] op_sel_hi:[1,0]
	s_nop 0
	v_mul_f32_e32 v117, 0xbfb8aa3b, v108
	v_exp_f32_e32 v117, v117
	v_add_u32_e32 v114, s26, v147
	v_mov_b32_e32 v115, v114
	v_add_f32_e32 v117, 1.0, v117
	v_rcp_f32_e32 v118, v117
	v_pk_mul_f32 v[104:105], v[104:105], v[116:117] op_sel_hi:[1,0]
	v_mul_f32_e32 v117, 0xbfb8aa3b, v109
	v_exp_f32_e32 v117, v117
	s_nop 0
	v_add_f32_e32 v117, 1.0, v117
	v_rcp_f32_e32 v119, v117
	v_pk_mul_f32 v[106:107], v[106:107], v[116:117] op_sel_hi:[1,0]
	v_pk_mul_f32 v[100:101], v[100:101], v[116:117] op_sel_hi:[1,0]
	v_pk_mul_f32 v[96:97], v[96:97], v[116:117] op_sel_hi:[1,0]
	v_pk_mul_f32 v[108:109], v[108:109], v[118:119]
	v_pk_mul_f32 v[98:99], v[98:99], v[116:117] op_sel_hi:[1,0]
	v_pk_mul_f32 v[104:105], v[104:105], v[108:109]
	v_pk_mul_f32 v[108:109], v[110:111], v[116:117] op_sel_hi:[1,0]
	s_nop 0
	v_mul_f32_e32 v110, 0xbfb8aa3b, v108
	v_mul_f32_e32 v111, 0xbfb8aa3b, v109
	v_exp_f32_e32 v110, v110
	v_exp_f32_e32 v111, v111
	v_add_f32_e32 v110, 1.0, v110
	v_add_f32_e32 v111, 1.0, v111
	v_rcp_f32_e32 v110, v110
	v_rcp_f32_e32 v111, v111
	s_nop 0
	v_pk_mul_f32 v[108:109], v[108:109], v[110:111]
	s_nop 0
	v_pk_mul_f32 v[106:107], v[106:107], v[108:109]
	v_mul_f32_e32 v108, 0xbfb8aa3b, v100
	v_mul_f32_e32 v109, 0xbfb8aa3b, v101
	v_exp_f32_e32 v108, v108
	v_exp_f32_e32 v109, v109
	v_add_f32_e32 v108, 1.0, v108
	v_add_f32_e32 v109, 1.0, v109
	v_rcp_f32_e32 v108, v108
	v_rcp_f32_e32 v109, v109
	s_nop 0
	v_pk_mul_f32 v[100:101], v[100:101], v[108:109]
	s_nop 0
	v_pk_mul_f32 v[100:101], v[96:97], v[100:101]
	v_pk_mul_f32 v[96:97], v[102:103], v[116:117] op_sel_hi:[1,0]
	s_nop 0
	v_mul_f32_e32 v102, 0xbfb8aa3b, v96
	v_mul_f32_e32 v103, 0xbfb8aa3b, v97
	v_exp_f32_e32 v102, v102
	v_exp_f32_e32 v103, v103
	v_add_f32_e32 v102, 1.0, v102
	v_add_f32_e32 v103, 1.0, v103
	v_rcp_f32_e32 v102, v102
	v_rcp_f32_e32 v103, v103
	s_nop 0
	v_pk_mul_f32 v[96:97], v[96:97], v[102:103]
	s_nop 0
	v_pk_mul_f32 v[102:103], v[98:99], v[96:97]
	v_cvt_pk_bf16_f32 v98, v100, v101
	v_mad_i64_i32 v[100:101], s[38:39], v115, s71, v[112:113]
	v_lshl_add_u64 v[100:101], v[100:101], 0, s[2:3]
	v_lshl_add_u64 v[100:101], v[100:101], 0, s[4:5]
	v_cvt_pk_bf16_f32 v96, v104, v105
	v_cvt_pk_bf16_f32 v97, v106, v107
	v_cvt_pk_bf16_f32 v99, v102, v103
	v_lshl_add_u64 v[100:101], v[100:101], 0, v[168:169]
	global_store_dwordx4 v[100:101], v[96:99], off
	ds_bpermute_b32 v98, v150, v141
	s_waitcnt lgkmcnt(0)
; __device__ __forceinline__ unsigned pk2(float lo, float hi) { f32x2_t v = {lo, hi}; bf16x2_t b = __builtin_convertvector(v, bf16x2_t); return __builtin_bit_cast(unsigned, b); }
; __device__ __forceinline__ float siluf_(float x) { return x * sigmoidf_(x); }
; #define RSTD_GET(ai, m) __int_as_float(__builtin_amdgcn_ds_bpermute(((m) * 16 + fr) << 2, __float_as_int((ai) ? es1 : es0)))
;     __device__ __forceinline__ void operator()(EPI_ARGS) const {
;     ...
;             for (int m = 0; m < 4; ++m) {
;                 int row = EPI_ROWS(ai, m); asm volatile("" : "+v"(row)); const float rs = RSTD_GET(ai, m);
;                 float o[8];
; #pragma unroll
;                 for (int n = 0; n < 2; ++n)
; #pragma unroll
;                     for (int e = 0; e < 4; ++e) { const float g = acc[ai][0][m][n][e] * rs, up = acc[ai][1][m][n][e] * rs; o[n * 4 + e] = siluf_(g) * up; }
;                 u32x4 w; w.x = pk2(o[0], o[1]); w.y = pk2(o[2], o[3]); w.z = pk2(o[4], o[5]); w.w = pk2(o[6], o[7]);
;                 *(u32x4*)(T + (size_t)row * FF + u.pn * 128 + wc * 32 + 8 * fq) = w;
	v_pk_mul_f32 v[92:93], v[92:93], v[98:99] op_sel_hi:[1,0]
	s_nop 0
	v_mul_f32_e32 v99, 0xbfb8aa3b, v92
	v_exp_f32_e32 v99, v99
	v_add_u32_e32 v96, s26, v149
	v_mov_b32_e32 v97, v96
	v_add_f32_e32 v99, 1.0, v99
	v_rcp_f32_e32 v100, v99
	v_pk_mul_f32 v[88:89], v[88:89], v[98:99] op_sel_hi:[1,0]
	v_mul_f32_e32 v99, 0xbfb8aa3b, v93
	v_exp_f32_e32 v99, v99
	s_nop 0
	v_add_f32_e32 v99, 1.0, v99
	v_rcp_f32_e32 v101, v99
	v_pk_mul_f32 v[90:91], v[90:91], v[98:99] op_sel_hi:[1,0]
	v_pk_mul_f32 v[84:85], v[84:85], v[98:99] op_sel_hi:[1,0]
	v_pk_mul_f32 v[80:81], v[80:81], v[98:99] op_sel_hi:[1,0]
	v_pk_mul_f32 v[92:93], v[92:93], v[100:101]
	v_pk_mul_f32 v[82:83], v[82:83], v[98:99] op_sel_hi:[1,0]
	v_pk_mul_f32 v[88:89], v[88:89], v[92:93]
	v_pk_mul_f32 v[92:93], v[94:95], v[98:99] op_sel_hi:[1,0]
	s_nop 0
	v_mul_f32_e32 v94, 0xbfb8aa3b, v92
	v_mul_f32_e32 v95, 0xbfb8aa3b, v93
	v_exp_f32_e32 v94, v94
	v_exp_f32_e32 v95, v95
	v_add_f32_e32 v94, 1.0, v94
	v_add_f32_e32 v95, 1.0, v95
	v_rcp_f32_e32 v94, v94
	v_rcp_f32_e32 v95, v95
	s_nop 0
	v_pk_mul_f32 v[92:93], v[92:93], v[94:95]
	s_nop 0
	v_pk_mul_f32 v[90:91], v[90:91], v[92:93]
	v_mul_f32_e32 v92, 0xbfb8aa3b, v84
	v_mul_f32_e32 v93, 0xbfb8aa3b, v85
	v_exp_f32_e32 v92, v92
	v_exp_f32_e32 v93, v93
	v_add_f32_e32 v92, 1.0, v92
	v_add_f32_e32 v93, 1.0, v93
	v_rcp_f32_e32 v92, v92
	v_rcp_f32_e32 v93, v93
	s_nop 0
	v_pk_mul_f32 v[84:85], v[84:85], v[92:93]
	s_nop 0
	v_pk_mul_f32 v[84:85], v[80:81], v[84:85]
	v_pk_mul_f32 v[80:81], v[86:87], v[98:99] op_sel_hi:[1,0]
	s_nop 0
	v_mul_f32_e32 v86, 0xbfb8aa3b, v80
	v_mul_f32_e32 v87, 0xbfb8aa3b, v81
	v_exp_f32_e32 v86, v86
	v_exp_f32_e32 v87, v87
	v_add_f32_e32 v86, 1.0, v86
	v_add_f32_e32 v87, 1.0, v87
	v_rcp_f32_e32 v86, v86
	v_rcp_f32_e32 v87, v87
	s_nop 0
	v_pk_mul_f32 v[80:81], v[80:81], v[86:87]
	s_nop 0
	v_pk_mul_f32 v[86:87], v[82:83], v[80:81]
	v_cvt_pk_bf16_f32 v82, v84, v85
	v_mad_i64_i32 v[84:85], s[38:39], v97, s71, v[112:113]
	v_lshl_add_u64 v[84:85], v[84:85], 0, s[2:3]
	v_lshl_add_u64 v[84:85], v[84:85], 0, s[4:5]
	v_cvt_pk_bf16_f32 v80, v88, v89
	v_cvt_pk_bf16_f32 v81, v90, v91
	v_cvt_pk_bf16_f32 v83, v86, v87
	v_lshl_add_u64 v[84:85], v[84:85], 0, v[168:169]
	global_store_dwordx4 v[84:85], v[80:83], off
	ds_bpermute_b32 v82, v152, v141
	s_waitcnt lgkmcnt(0)
	v_pk_mul_f32 v[76:77], v[76:77], v[82:83] op_sel_hi:[1,0]
	s_nop 0
	v_mul_f32_e32 v83, 0xbfb8aa3b, v76
	v_exp_f32_e32 v83, v83
	v_add_u32_e32 v80, s26, v151
	v_mov_b32_e32 v81, v80
	v_add_f32_e32 v83, 1.0, v83
	v_rcp_f32_e32 v84, v83
	v_pk_mul_f32 v[72:73], v[72:73], v[82:83] op_sel_hi:[1,0]
	v_mul_f32_e32 v83, 0xbfb8aa3b, v77
	v_exp_f32_e32 v83, v83
	s_nop 0
	v_add_f32_e32 v83, 1.0, v83
	v_rcp_f32_e32 v85, v83
	v_pk_mul_f32 v[74:75], v[74:75], v[82:83] op_sel_hi:[1,0]
	v_pk_mul_f32 v[68:69], v[68:69], v[82:83] op_sel_hi:[1,0]
	v_pk_mul_f32 v[64:65], v[64:65], v[82:83] op_sel_hi:[1,0]
	v_pk_mul_f32 v[76:77], v[76:77], v[84:85]
	v_pk_mul_f32 v[66:67], v[66:67], v[82:83] op_sel_hi:[1,0]
	v_pk_mul_f32 v[72:73], v[72:73], v[76:77]
	v_pk_mul_f32 v[76:77], v[78:79], v[82:83] op_sel_hi:[1,0]
	s_nop 0
	v_mul_f32_e32 v78, 0xbfb8aa3b, v76
	v_mul_f32_e32 v79, 0xbfb8aa3b, v77
	v_exp_f32_e32 v78, v78
	v_exp_f32_e32 v79, v79
	v_add_f32_e32 v78, 1.0, v78
	v_add_f32_e32 v79, 1.0, v79
	v_rcp_f32_e32 v78, v78
	v_rcp_f32_e32 v79, v79
	s_nop 0
	v_pk_mul_f32 v[76:77], v[76:77], v[78:79]
	s_nop 0
	v_pk_mul_f32 v[74:75], v[74:75], v[76:77]
	v_mul_f32_e32 v76, 0xbfb8aa3b, v68
	v_mul_f32_e32 v77, 0xbfb8aa3b, v69
	v_exp_f32_e32 v76, v76
	v_exp_f32_e32 v77, v77
	v_add_f32_e32 v76, 1.0, v76
	v_add_f32_e32 v77, 1.0, v77
	v_rcp_f32_e32 v76, v76
	v_rcp_f32_e32 v77, v77
	s_nop 0
	v_pk_mul_f32 v[68:69], v[68:69], v[76:77]
	s_nop 0
	v_pk_mul_f32 v[68:69], v[64:65], v[68:69]
	v_pk_mul_f32 v[64:65], v[70:71], v[82:83] op_sel_hi:[1,0]
	s_nop 0
	v_mul_f32_e32 v70, 0xbfb8aa3b, v64
	v_mul_f32_e32 v71, 0xbfb8aa3b, v65
	v_exp_f32_e32 v70, v70
	v_exp_f32_e32 v71, v71
	v_add_f32_e32 v70, 1.0, v70
	v_add_f32_e32 v71, 1.0, v71
	v_rcp_f32_e32 v70, v70
	v_rcp_f32_e32 v71, v71
	s_nop 0
	v_pk_mul_f32 v[64:65], v[64:65], v[70:71]
	s_nop 0
	v_pk_mul_f32 v[70:71], v[66:67], v[64:65]
	v_cvt_pk_bf16_f32 v66, v68, v69
	v_mad_i64_i32 v[68:69], s[26:27], v81, s71, v[112:113]
	v_lshl_add_u64 v[68:69], v[68:69], 0, s[2:3]
	v_lshl_add_u64 v[68:69], v[68:69], 0, s[4:5]
	v_cvt_pk_bf16_f32 v64, v72, v73
	v_cvt_pk_bf16_f32 v65, v74, v75
	v_cvt_pk_bf16_f32 v67, v70, v71
	v_lshl_add_u64 v[68:69], v[68:69], 0, v[168:169]
	global_store_dwordx4 v[68:69], v[64:67], off
	ds_bpermute_b32 v64, v145, v140
	s_nop 0
	v_add_u32_e32 v65, 0x80, v154
	s_waitcnt lgkmcnt(0)
; __device__ __forceinline__ unsigned pk2(float lo, float hi) { f32x2_t v = {lo, hi}; bf16x2_t b = __builtin_convertvector(v, bf16x2_t); return __builtin_bit_cast(unsigned, b); }
; __device__ __forceinline__ float siluf_(float x) { return x * sigmoidf_(x); }
; #define RSTD_GET(ai, m) __int_as_float(__builtin_amdgcn_ds_bpermute(((m) * 16 + fr) << 2, __float_as_int((ai) ? es1 : es0)))
;     __device__ __forceinline__ void operator()(EPI_ARGS) const {
;     ...
;             for (int m = 0; m < 4; ++m) {
;                 int row = EPI_ROWS(ai, m); asm volatile("" : "+v"(row)); const float rs = RSTD_GET(ai, m);
;                 float o[8];
; #pragma unroll
;                 for (int n = 0; n < 2; ++n)
; #pragma unroll
;                     for (int e = 0; e < 4; ++e) { const float g = acc[ai][0][m][n][e] * rs, up = acc[ai][1][m][n][e] * rs; o[n * 4 + e] = siluf_(g) * up; }
;                 u32x4 w; w.x = pk2(o[0], o[1]); w.y = pk2(o[2], o[3]); w.z = pk2(o[4], o[5]); w.w = pk2(o[6], o[7]);
;                 *(u32x4*)(T + (size_t)row * FF + u.pn * 128 + wc * 32 + 8 * fq) = w;
	v_pk_mul_f32 v[60:61], v[60:61], v[64:65] op_sel_hi:[1,0]
	v_pk_mul_f32 v[56:57], v[56:57], v[64:65] op_sel_hi:[1,0]
	v_mul_f32_e32 v66, 0xbfb8aa3b, v60
	v_mul_f32_e32 v67, 0xbfb8aa3b, v61
	v_exp_f32_e32 v66, v66
	v_exp_f32_e32 v67, v67
	v_pk_mul_f32 v[58:59], v[58:59], v[64:65] op_sel_hi:[1,0]
	v_pk_mul_f32 v[52:53], v[52:53], v[64:65] op_sel_hi:[1,0]
	v_add_f32_e32 v66, 1.0, v66
	v_add_f32_e32 v67, 1.0, v67
	v_rcp_f32_e32 v66, v66
	v_rcp_f32_e32 v67, v67
	v_pk_mul_f32 v[48:49], v[48:49], v[64:65] op_sel_hi:[1,0]
	v_pk_mul_f32 v[50:51], v[50:51], v[64:65] op_sel_hi:[1,0]
	v_pk_mul_f32 v[60:61], v[60:61], v[66:67]
	s_nop 0
	v_pk_mul_f32 v[56:57], v[56:57], v[60:61]
	v_pk_mul_f32 v[60:61], v[62:63], v[64:65] op_sel_hi:[1,0]
	s_nop 0
	v_mul_f32_e32 v62, 0xbfb8aa3b, v60
	v_mul_f32_e32 v63, 0xbfb8aa3b, v61
	v_exp_f32_e32 v62, v62
	v_exp_f32_e32 v63, v63
	v_add_f32_e32 v62, 1.0, v62
	v_add_f32_e32 v63, 1.0, v63
	v_rcp_f32_e32 v62, v62
	v_rcp_f32_e32 v63, v63
	s_nop 0
	v_pk_mul_f32 v[60:61], v[60:61], v[62:63]
	s_nop 0
	v_pk_mul_f32 v[58:59], v[58:59], v[60:61]
	v_mul_f32_e32 v60, 0xbfb8aa3b, v52
	v_mul_f32_e32 v61, 0xbfb8aa3b, v53
	v_exp_f32_e32 v60, v60
	v_exp_f32_e32 v61, v61
	v_add_f32_e32 v60, 1.0, v60
	v_add_f32_e32 v61, 1.0, v61
	v_rcp_f32_e32 v60, v60
	v_rcp_f32_e32 v61, v61
	s_nop 0
	v_pk_mul_f32 v[52:53], v[52:53], v[60:61]
	s_nop 0
	v_pk_mul_f32 v[52:53], v[48:49], v[52:53]
	v_pk_mul_f32 v[48:49], v[54:55], v[64:65] op_sel_hi:[1,0]
	s_nop 0
	v_mul_f32_e32 v54, 0xbfb8aa3b, v48
	v_mul_f32_e32 v55, 0xbfb8aa3b, v49
	v_exp_f32_e32 v54, v54
	v_exp_f32_e32 v55, v55
	v_add_f32_e32 v54, 1.0, v54
	v_add_f32_e32 v55, 1.0, v55
	v_rcp_f32_e32 v54, v54
	v_rcp_f32_e32 v55, v55
	s_nop 0
	v_pk_mul_f32 v[48:49], v[48:49], v[54:55]
	s_nop 0
	v_pk_mul_f32 v[54:55], v[50:51], v[48:49]
	v_cvt_pk_bf16_f32 v50, v52, v53
	v_mad_i64_i32 v[52:53], s[26:27], v65, s71, v[112:113]
	v_lshl_add_u64 v[52:53], v[52:53], 0, s[2:3]
	v_lshl_add_u64 v[52:53], v[52:53], 0, s[4:5]
	v_cvt_pk_bf16_f32 v48, v56, v57
	v_cvt_pk_bf16_f32 v49, v58, v59
	v_cvt_pk_bf16_f32 v51, v54, v55
	v_lshl_add_u64 v[52:53], v[52:53], 0, v[168:169]
	global_store_dwordx4 v[52:53], v[48:51], off
	ds_bpermute_b32 v48, v148, v140
	s_nop 0
	v_add_u32_e32 v49, 0x80, v114
	s_waitcnt lgkmcnt(0)
	v_pk_mul_f32 v[44:45], v[44:45], v[48:49] op_sel_hi:[1,0]
	v_pk_mul_f32 v[40:41], v[40:41], v[48:49] op_sel_hi:[1,0]
	v_mul_f32_e32 v50, 0xbfb8aa3b, v44
	v_mul_f32_e32 v51, 0xbfb8aa3b, v45
	v_exp_f32_e32 v50, v50
	v_exp_f32_e32 v51, v51
	v_pk_mul_f32 v[42:43], v[42:43], v[48:49] op_sel_hi:[1,0]
	v_pk_mul_f32 v[36:37], v[36:37], v[48:49] op_sel_hi:[1,0]
	v_add_f32_e32 v50, 1.0, v50
	v_add_f32_e32 v51, 1.0, v51
	v_rcp_f32_e32 v50, v50
	v_rcp_f32_e32 v51, v51
	v_pk_mul_f32 v[32:33], v[32:33], v[48:49] op_sel_hi:[1,0]
	v_pk_mul_f32 v[34:35], v[34:35], v[48:49] op_sel_hi:[1,0]
	v_pk_mul_f32 v[44:45], v[44:45], v[50:51]
	s_nop 0
	v_pk_mul_f32 v[40:41], v[40:41], v[44:45]
	v_pk_mul_f32 v[44:45], v[46:47], v[48:49] op_sel_hi:[1,0]
	s_nop 0
	v_mul_f32_e32 v46, 0xbfb8aa3b, v44
	v_mul_f32_e32 v47, 0xbfb8aa3b, v45
	v_exp_f32_e32 v46, v46
	v_exp_f32_e32 v47, v47
	v_add_f32_e32 v46, 1.0, v46
	v_add_f32_e32 v47, 1.0, v47
	v_rcp_f32_e32 v46, v46
	v_rcp_f32_e32 v47, v47
	s_nop 0
	v_pk_mul_f32 v[44:45], v[44:45], v[46:47]
	s_nop 0
	v_pk_mul_f32 v[42:43], v[42:43], v[44:45]
	v_mul_f32_e32 v44, 0xbfb8aa3b, v36
	v_mul_f32_e32 v45, 0xbfb8aa3b, v37
	v_exp_f32_e32 v44, v44
	v_exp_f32_e32 v45, v45
	v_add_f32_e32 v44, 1.0, v44
	v_add_f32_e32 v45, 1.0, v45
	v_rcp_f32_e32 v44, v44
	v_rcp_f32_e32 v45, v45
	s_nop 0
	v_pk_mul_f32 v[36:37], v[36:37], v[44:45]
	s_nop 0
	v_pk_mul_f32 v[36:37], v[32:33], v[36:37]
	v_pk_mul_f32 v[32:33], v[38:39], v[48:49] op_sel_hi:[1,0]
	s_nop 0
	v_mul_f32_e32 v38, 0xbfb8aa3b, v32
	v_mul_f32_e32 v39, 0xbfb8aa3b, v33
	v_exp_f32_e32 v38, v38
	v_exp_f32_e32 v39, v39
	v_add_f32_e32 v38, 1.0, v38
	v_add_f32_e32 v39, 1.0, v39
	v_rcp_f32_e32 v38, v38
	v_rcp_f32_e32 v39, v39
	s_nop 0
	v_pk_mul_f32 v[32:33], v[32:33], v[38:39]
	s_nop 0
	v_pk_mul_f32 v[38:39], v[34:35], v[32:33]
	v_cvt_pk_bf16_f32 v34, v36, v37
	v_mad_i64_i32 v[36:37], s[26:27], v49, s71, v[112:113]
	v_lshl_add_u64 v[36:37], v[36:37], 0, s[2:3]
	v_lshl_add_u64 v[36:37], v[36:37], 0, s[4:5]
	v_cvt_pk_bf16_f32 v32, v40, v41
	v_cvt_pk_bf16_f32 v33, v42, v43
	v_cvt_pk_bf16_f32 v35, v38, v39
	v_lshl_add_u64 v[36:37], v[36:37], 0, v[168:169]
	global_store_dwordx4 v[36:37], v[32:35], off
	ds_bpermute_b32 v32, v150, v140
	s_nop 0
	v_add_u32_e32 v33, 0x80, v96
	s_waitcnt lgkmcnt(0)
; __device__ __forceinline__ unsigned pk2(float lo, float hi) { f32x2_t v = {lo, hi}; bf16x2_t b = __builtin_convertvector(v, bf16x2_t); return __builtin_bit_cast(unsigned, b); }
; __device__ __forceinline__ float siluf_(float x) { return x * sigmoidf_(x); }
; #define RSTD_GET(ai, m) __int_as_float(__builtin_amdgcn_ds_bpermute(((m) * 16 + fr) << 2, __float_as_int((ai) ? es1 : es0)))
; __device__ __forceinline__ float row_rstd(const float* SS, int row) {
;     const f32x4* p = (const f32x4*)(SS + (size_t)row * 32);
;     float s = 0.f;
; #pragma unroll
;     for (int j = 0; j < 8; ++j) { const f32x4 a = p[j]; s += (a[0] + a[1]) + (a[2] + a[3]); }
;     return rsqrtf(s * (1.f / 1024.f) + EPS);
; }
;     __device__ __forceinline__ void operator()(EPI_ARGS) const {
;     ...
;             for (int m = 0; m < 4; ++m) {
;                 int row = EPI_ROWS(ai, m); asm volatile("" : "+v"(row)); const float rs = RSTD_GET(ai, m);
;                 float o[8];
; #pragma unroll
;                 for (int n = 0; n < 2; ++n)
; #pragma unroll
;                     for (int e = 0; e < 4; ++e) { const float g = acc[ai][0][m][n][e] * rs, up = acc[ai][1][m][n][e] * rs; o[n * 4 + e] = siluf_(g) * up; }
;                 u32x4 w; w.x = pk2(o[0], o[1]); w.y = pk2(o[2], o[3]); w.z = pk2(o[4], o[5]); w.w = pk2(o[6], o[7]);
;                 *(u32x4*)(T + (size_t)row * FF + u.pn * 128 + wc * 32 + 8 * fq) = w;
	v_pk_mul_f32 v[28:29], v[28:29], v[32:33] op_sel_hi:[1,0]
	v_pk_mul_f32 v[24:25], v[24:25], v[32:33] op_sel_hi:[1,0]
	v_mul_f32_e32 v34, 0xbfb8aa3b, v28
	v_mul_f32_e32 v35, 0xbfb8aa3b, v29
	v_exp_f32_e32 v34, v34
	v_exp_f32_e32 v35, v35
	v_pk_mul_f32 v[26:27], v[26:27], v[32:33] op_sel_hi:[1,0]
	v_pk_mul_f32 v[20:21], v[20:21], v[32:33] op_sel_hi:[1,0]
	v_add_f32_e32 v34, 1.0, v34
	v_add_f32_e32 v35, 1.0, v35
	v_rcp_f32_e32 v34, v34
	v_rcp_f32_e32 v35, v35
	v_pk_mul_f32 v[16:17], v[16:17], v[32:33] op_sel_hi:[1,0]
	v_pk_mul_f32 v[18:19], v[18:19], v[32:33] op_sel_hi:[1,0]
	v_pk_mul_f32 v[28:29], v[28:29], v[34:35]
	s_nop 0
	v_pk_mul_f32 v[24:25], v[24:25], v[28:29]
	v_pk_mul_f32 v[28:29], v[30:31], v[32:33] op_sel_hi:[1,0]
	s_nop 0
	v_mul_f32_e32 v30, 0xbfb8aa3b, v28
	v_mul_f32_e32 v31, 0xbfb8aa3b, v29
	v_exp_f32_e32 v30, v30
	v_exp_f32_e32 v31, v31
	v_add_f32_e32 v30, 1.0, v30
	v_add_f32_e32 v31, 1.0, v31
	v_rcp_f32_e32 v30, v30
	v_rcp_f32_e32 v31, v31
	s_nop 0
	v_pk_mul_f32 v[28:29], v[28:29], v[30:31]
	s_nop 0
	v_pk_mul_f32 v[26:27], v[26:27], v[28:29]
	v_mul_f32_e32 v28, 0xbfb8aa3b, v20
	v_mul_f32_e32 v29, 0xbfb8aa3b, v21
	v_exp_f32_e32 v28, v28
	v_exp_f32_e32 v29, v29
	v_add_f32_e32 v28, 1.0, v28
	v_add_f32_e32 v29, 1.0, v29
	v_rcp_f32_e32 v28, v28
	v_rcp_f32_e32 v29, v29
	s_nop 0
	v_pk_mul_f32 v[20:21], v[20:21], v[28:29]
	s_nop 0
	v_pk_mul_f32 v[20:21], v[16:17], v[20:21]
	v_pk_mul_f32 v[16:17], v[22:23], v[32:33] op_sel_hi:[1,0]
	s_nop 0
	v_mul_f32_e32 v22, 0xbfb8aa3b, v16
	v_mul_f32_e32 v23, 0xbfb8aa3b, v17
	v_exp_f32_e32 v22, v22
	v_exp_f32_e32 v23, v23
	v_add_f32_e32 v22, 1.0, v22
	v_add_f32_e32 v23, 1.0, v23
	v_rcp_f32_e32 v22, v22
	v_rcp_f32_e32 v23, v23
	s_nop 0
	v_pk_mul_f32 v[16:17], v[16:17], v[22:23]
	s_nop 0
	v_pk_mul_f32 v[22:23], v[18:19], v[16:17]
	v_cvt_pk_bf16_f32 v18, v20, v21
	v_mad_i64_i32 v[20:21], s[26:27], v33, s71, v[112:113]
	v_lshl_add_u64 v[20:21], v[20:21], 0, s[2:3]
	v_lshl_add_u64 v[20:21], v[20:21], 0, s[4:5]
	v_cvt_pk_bf16_f32 v16, v24, v25
	v_cvt_pk_bf16_f32 v17, v26, v27
	v_cvt_pk_bf16_f32 v19, v22, v23
	v_lshl_add_u64 v[20:21], v[20:21], 0, v[168:169]
	global_store_dwordx4 v[20:21], v[16:19], off
	ds_bpermute_b32 v16, v152, v140
	s_nop 0
	v_add_u32_e32 v17, 0x80, v80
	s_waitcnt lgkmcnt(0)
	v_pk_mul_f32 v[12:13], v[12:13], v[16:17] op_sel_hi:[1,0]
	v_pk_mul_f32 v[8:9], v[8:9], v[16:17] op_sel_hi:[1,0]
	v_mul_f32_e32 v18, 0xbfb8aa3b, v12
	v_mul_f32_e32 v19, 0xbfb8aa3b, v13
	v_exp_f32_e32 v18, v18
	v_exp_f32_e32 v19, v19
	v_pk_mul_f32 v[10:11], v[10:11], v[16:17] op_sel_hi:[1,0]
	v_pk_mul_f32 v[4:5], v[4:5], v[16:17] op_sel_hi:[1,0]
	v_add_f32_e32 v18, 1.0, v18
	v_add_f32_e32 v19, 1.0, v19
	v_rcp_f32_e32 v18, v18
	v_rcp_f32_e32 v19, v19
	v_pk_mul_f32 v[0:1], v[0:1], v[16:17] op_sel_hi:[1,0]
	v_pk_mul_f32 v[2:3], v[2:3], v[16:17] op_sel_hi:[1,0]
	v_pk_mul_f32 v[12:13], v[12:13], v[18:19]
	s_nop 0
	v_pk_mul_f32 v[8:9], v[8:9], v[12:13]
	v_pk_mul_f32 v[12:13], v[14:15], v[16:17] op_sel_hi:[1,0]
	s_nop 0
	v_mul_f32_e32 v14, 0xbfb8aa3b, v12
	v_mul_f32_e32 v15, 0xbfb8aa3b, v13
	v_exp_f32_e32 v14, v14
	v_exp_f32_e32 v15, v15
	v_add_f32_e32 v14, 1.0, v14
	v_add_f32_e32 v15, 1.0, v15
	v_rcp_f32_e32 v14, v14
	v_rcp_f32_e32 v15, v15
	s_nop 0
	v_pk_mul_f32 v[12:13], v[12:13], v[14:15]
	s_nop 0
	v_pk_mul_f32 v[10:11], v[10:11], v[12:13]
	v_mul_f32_e32 v12, 0xbfb8aa3b, v4
	v_mul_f32_e32 v13, 0xbfb8aa3b, v5
	v_exp_f32_e32 v12, v12
	v_exp_f32_e32 v13, v13
	v_add_f32_e32 v12, 1.0, v12
	v_add_f32_e32 v13, 1.0, v13
	v_rcp_f32_e32 v12, v12
	v_rcp_f32_e32 v13, v13
	s_nop 0
	v_pk_mul_f32 v[4:5], v[4:5], v[12:13]
	s_nop 0
	v_pk_mul_f32 v[4:5], v[0:1], v[4:5]
	v_pk_mul_f32 v[0:1], v[6:7], v[16:17] op_sel_hi:[1,0]
	s_nop 0
	v_mul_f32_e32 v6, 0xbfb8aa3b, v0
	v_mul_f32_e32 v7, 0xbfb8aa3b, v1
	v_exp_f32_e32 v6, v6
	v_exp_f32_e32 v7, v7
	v_add_f32_e32 v6, 1.0, v6
	v_add_f32_e32 v7, 1.0, v7
	v_rcp_f32_e32 v6, v6
	v_rcp_f32_e32 v7, v7
	s_nop 0
	v_pk_mul_f32 v[0:1], v[0:1], v[6:7]
	s_nop 0
	v_pk_mul_f32 v[6:7], v[2:3], v[0:1]
	v_cvt_pk_bf16_f32 v2, v4, v5
	v_mad_i64_i32 v[4:5], s[26:27], v17, s71, v[112:113]
	v_lshl_add_u64 v[4:5], v[4:5], 0, s[2:3]
	v_lshl_add_u64 v[4:5], v[4:5], 0, s[4:5]
	v_cvt_pk_bf16_f32 v0, v8, v9
	v_cvt_pk_bf16_f32 v1, v10, v11
	v_cvt_pk_bf16_f32 v3, v6, v7
	v_lshl_add_u64 v[4:5], v[4:5], 0, v[168:169]
	s_mov_b64 s[2:3], -1
	global_store_dwordx4 v[4:5], v[0:3], off
	s_cbranch_vccnz .LBB0_891
	s_waitcnt vmcnt(8)
	v_add_f32_e32 v4, v204, v205
	v_add_f32_e32 v6, v236, v237
	v_add_f32_e32 v5, v206, v207
	v_add_f32_e32 v7, v238, v239
	v_add_f32_e32 v1, v4, v5
	v_add_f32_e32 v0, v6, v7
	v_add_f32_e32 v1, 0, v1
	v_add_f32_e32 v0, 0, v0
	v_add_f32_e32 v4, v208, v209
	v_add_f32_e32 v6, v240, v241
	v_add_f32_e32 v5, v210, v211
	v_add_f32_e32 v7, v242, v243
	v_add_f32_e32 v4, v4, v5
	v_add_f32_e32 v6, v6, v7
	v_add_f32_e32 v1, v1, v4
	v_add_f32_e32 v0, v0, v6
	v_add_f32_e32 v4, v212, v213
	v_add_f32_e32 v6, v180, v181
	v_add_f32_e32 v5, v214, v215
	v_add_f32_e32 v7, v182, v183
	v_add_f32_e32 v4, v4, v5
	v_add_f32_e32 v6, v6, v7
	v_add_f32_e32 v1, v1, v4
	v_add_f32_e32 v0, v0, v6
	v_add_f32_e32 v4, v216, v217
	v_add_f32_e32 v6, v184, v185
	v_add_f32_e32 v5, v218, v219
	v_add_f32_e32 v7, v186, v187
	v_add_f32_e32 v4, v4, v5
	v_add_f32_e32 v6, v6, v7
	v_add_f32_e32 v1, v1, v4
	v_add_f32_e32 v0, v0, v6
	v_add_f32_e32 v4, v220, v221
	v_add_f32_e32 v6, v190, v191
	v_add_f32_e32 v5, v222, v223
	v_add_f32_e32 v7, v192, v193
	v_add_f32_e32 v4, v4, v5
	v_add_f32_e32 v6, v6, v7
	v_add_f32_e32 v1, v1, v4
	v_add_f32_e32 v0, v0, v6
	v_add_f32_e32 v4, v224, v225
	v_add_f32_e32 v6, v194, v195
	v_add_f32_e32 v5, v226, v227
	v_add_f32_e32 v7, v196, v197
	v_add_f32_e32 v4, v4, v5
	v_add_f32_e32 v6, v6, v7
	v_add_f32_e32 v1, v1, v4
	v_add_f32_e32 v0, v0, v6
	v_add_f32_e32 v4, v228, v229
	v_add_f32_e32 v6, v160, v161
	v_add_f32_e32 v5, v230, v231
	v_add_f32_e32 v7, v162, v163
	v_add_f32_e32 v4, v4, v5
	v_add_f32_e32 v6, v6, v7
	v_add_f32_e32 v1, v1, v4
	v_add_f32_e32 v0, v0, v6
	v_add_f32_e32 v4, v232, v233
	v_add_f32_e32 v6, v244, v245
	v_add_f32_e32 v5, v234, v235
	v_add_f32_e32 v7, v246, v247
	v_add_f32_e32 v4, v4, v5
	v_add_f32_e32 v6, v6, v7
	v_add_f32_e32 v1, v1, v4
	v_add_f32_e32 v0, v0, v6
	s_mov_b32 s2, 0x3a800000
	s_andn2_b64 vcc, exec, s[22:23]
	s_nop 0
	v_pk_fma_f32 v[0:1], v[0:1], s[2:3], v[170:171] op_sel_hi:[1,0,0]
	s_nop 0
	v_cmp_gt_f32_e64 s[36:37], s33, v0
	v_cmp_gt_f32_e64 s[38:39], s33, v1
	s_cbranch_vccnz .LBB0_890
	s_barrier
	s_branch .LBB0_890
